# speedup vs baseline: 1.0040x; 1.0040x over previous
; __device__ __forceinline__ void side_transpose(KP p, char* smem, int bid, int nb, int wv, const int part) {
;     ...
;   int j = (all / 4) * part + bid * 6 + (wv - 2);
;   if (j >= tot) return;
; __global__ void __launch_bounds__(NT) mega(Params pv) {
;     ...
;     } else {
;       char* wa = smem + WORK_OFF + (wv - 2) * WLDS_B;
;       if (seg < 3) {
;         { KP p = kparams(); hgrn_pre_phase(p, wa, wv, seg + 1, bid * 6 + (wv - 2), nb * 6); }
;         { KP p = kparams(); gdn_pre_phase(p, wa, wv, seg + 1, bid * 6 + (wv - 2), nb * 6); }
;       }
;       { KP p = kparams(); side_transpose(p, smem, bid, nb, wv, seg); }
.LBB0_847:
	v_readlane_b32 s4, v253, 11
	v_readlane_b32 s5, v253, 12
	s_and_b64 vcc, exec, s[4:5]
	s_mov_b64 s[4:5], -1
	s_cbranch_vccz .LBB0_903
	v_readlane_b32 s6, v253, 17
	s_nop 3
	s_and_b32 s6, s6, 1
	s_cmp_eq_u32 s6, 0
	s_cbranch_scc1 .Ld1_done

; #define tidx() tidx_(wv)
; __device__ __forceinline__ void hgrn_pre_phase(KP p, char* smem, int wv, const int seg, const int gw, const int nw) {
;   const int lane = tidx() & 63, fr = lane & 15, fq = lane >> 4;
;   unsigned short* wl = (unsigned short*)smem;
;   char* scr = (char*)p->Wt1;
;   for (int idx = gw; idx < 2048; idx += nw) {
;     const int bh = idx >> 6, c = seg * 64 + (idx & 63), task = bh * 256 + c, b = bh >> 4, h = bh & 15;
;     const long r0 = (long)b * SEQ + c * 16;
;     const float* qsrc = p->proj + r0 * PW + h * 128 + lane * 2;
;     float2 qv[16], fv[16];
; #pragma unroll
;     for (int i = 0; i < 16; ++i) { qv[i] = *(const float2*)(qsrc + (long)i * PW); fv[i] = *(const float2*)(qsrc + 2048 + (long)i * PW); }
;     float lb0[16], lb1[16];
;     float c0 = 0.f, c1 = 0.f;
; #pragma unroll
;     for (int i = 0; i < 16; ++i) { c0 += __logf(fv[i].x); c1 += __logf(fv[i].y); lb0[i] = c0; lb1[i] = c1; }
;     char* tb = scr + (long)task * HG_TASK_B;
;     *(float2*)(tb + 8704 + lane * 8) = make_float2(__expf(c0), __expf(c1));
;     unsigned short kh0[16], kh1[16];
;     const float ec0 = __expf(c0), ec1 = __expf(c1);
; #pragma unroll
;     for (int i = 0; i < 16; ++i) {
;       const float e0 = __expf(lb0[i]), e1 = __expf(lb1[i]);
;       const float k0 = (1.f - fv[i].x) * __frcp_rn(e0), k1 = (1.f - fv[i].y) * __frcp_rn(e1);
;       const unsigned qt = (unsigned)f2bf(qv[i].x * e0) | ((unsigned)f2bf(qv[i].y * e1) << 16);
;       const unsigned kt = (unsigned)f2bf(k0) | ((unsigned)f2bf(k1) << 16);
;       *(unsigned*)(wl + i * 136 + lane * 2) = qt;
;       *(unsigned*)(wl + 2176 + i * 136 + lane * 2) = kt;
.Ld1_done:
	v_readlane_b32 s6, v253, 42
	s_or_b32 s0, s6, 1
	v_readlane_b32 s6, v253, 49
	v_readlane_b32 s7, v253, 50
	s_mov_b64 s[4:5], s[86:87]
	s_and_b64 vcc, exec, s[6:7]
	s_mov_b32 s1, 0x10000
	s_mov_b32 s2, 0x1c000
	s_mov_b32 s3, 0x1e000
	s_mov_b32 s34, 0x2a000
	s_mov_b32 s35, 0x2c000
	s_mov_b32 s29, 0x38000
	s_mov_b32 s40, 0x3a000
	s_mov_b32 s42, 0x46000
	s_mov_b32 s44, 0x48000
	s_mov_b32 s45, 0x54000
	s_mov_b32 s50, 0x56000
	s_mov_b32 s51, 0x62000
	s_mov_b32 s52, 0x64000
	s_mov_b32 s82, 0x70000
	s_mov_b32 s83, 0x72000
	s_mov_b32 s88, 0x7e000
	s_mov_b32 s89, 0x80000
	s_mov_b32 s90, 0x8c000
	s_mov_b32 s91, 0x8e000
	s_mov_b32 s92, 0x9a000
	s_mov_b32 s93, 0x9c000
	s_mov_b32 s94, 0xa8000
	s_mov_b32 s95, 0xaa000
	s_mov_b32 s18, 0xb6000
	s_mov_b32 s86, 0xb8000
	s_mov_b32 s87, 0xc4000
	s_mov_b32 s25, 0xc6000
	s_mov_b32 s26, 0xd2000
	s_mov_b32 s27, 0xd4000
	s_movk_i32 s28, 0x1000
	s_mov_b64 s[30:31], 0x1000
	v_mbcnt_lo_u32_b32 v2, -1, 0
	v_mbcnt_hi_u32_b32 v2, -1, v2
	s_cbranch_vccnz .LBB0_851
	v_and_b32_e32 v5, 63, v2
	v_lshlrev_b32_e32 v4, 1, v5
	s_load_dwordx2 s[14:15], s[4:5], 0x88
	s_load_dwordx2 s[16:17], s[4:5], 0xc0
	v_lshlrev_b32_e32 v6, 2, v2
	v_and_b32_e32 v7, 14, v4
	s_movk_i32 s5, 0xe0
	v_and_b32_e32 v3, 15, v2
	v_and_or_b32 v6, v6, s5, v7
	v_lshlrev_b32_e32 v18, 4, v6
	v_mul_u32_u24_e32 v6, 0x88, v3
	v_readlane_b32 s4, v253, 13
	v_lshlrev_b32_e32 v6, 1, v6
	v_and_b32_e32 v7, 48, v2
	v_lshlrev_b32_e32 v0, 3, v5
	v_lshl_add_u32 v74, v5, 2, s4
	v_add3_u32 v75, s4, v6, v7
	v_lshlrev_b32_e32 v20, 4, v5
	v_lshrrev_b32_e32 v5, 2, v2
	v_lshlrev_b32_e32 v6, 1, v2
	v_and_b32_e32 v5, 12, v5
	v_and_b32_e32 v7, 16, v6
	v_and_b32_e32 v9, 7, v2
	v_cmp_gt_u32_e64 s[4:5], v3, v5
	v_or_b32_e32 v2, v5, v7
	v_or_b32_e32 v6, 1, v5
	v_or_b32_e32 v8, 2, v5
	v_or_b32_e32 v5, 3, v5
	v_cmp_gt_u32_e64 s[6:7], v3, v6
	v_or_b32_e32 v6, v6, v7
	v_cmp_gt_u32_e64 s[8:9], v3, v8
	v_or_b32_e32 v8, v8, v7
	v_cmp_gt_u32_e64 s[10:11], v3, v5
	v_or_b32_e32 v3, v5, v7
	v_lshl_or_b32 v2, v2, 3, v9
	v_lshl_or_b32 v6, v6, 3, v9
	v_lshl_or_b32 v8, v8, 3, v9
	v_lshl_or_b32 v10, v3, 3, v9
	s_lshl_b32 s19, s0, 6
	v_mov_b32_e32 v19, v1
	v_mov_b32_e32 v21, v1
	v_lshlrev_b32_e32 v22, 2, v4
	v_mov_b32_e32 v23, v1
	v_lshlrev_b32_e32 v76, 1, v2
	v_lshlrev_b32_e32 v77, 1, v6
	v_lshlrev_b32_e32 v78, 1, v8
	v_lshlrev_b32_e32 v79, 1, v10
	v_add_u32_e32 v80, 0x1000, v74
	v_add_u32_e32 v81, 0x1200, v74
	v_add_u32_e32 v82, 0x400, v74
	v_add_u32_e32 v83, 0x1400, v74
	v_add_u32_e32 v84, 0x1600, v74
	v_add_u32_e32 v85, 0x800, v74
	v_add_u32_e32 v86, 0x1800, v74
	v_add_u32_e32 v87, 0x1a00, v74
	v_add_u32_e32 v88, 0xc00, v74
	v_add_u32_e32 v89, 0x1c00, v74
	v_add_u32_e32 v90, 0x1e00, v74
	v_readlane_b32 s20, v253, 17

; __device__ __forceinline__ SideJob side_job(KP p, const int j) {
;   const int t2 = 64 * 128, t3 = 64 * 688;
;   SideJob r;
;   if (j < t2) { r.W = p->w_out; r.Wt = p->Wt2; r.K = D; r.N = D; r.k0 = (j >> 7) * 64; r.n0 = (j & 127) * 32; }
;   else if (j < t2 + t3) { const int q = j - t2; r.W = p->w_ffn_in; r.Wt = p->Wt3; r.K = D; r.N = DFF2; r.k0 = (q / 688) * 64; r.n0 = (q % 688) * 32; }
;   else { const int q = j - t2 - t3; r.W = p->w_ffn_out; r.Wt = p->Wt4; r.K = DFF; r.N = D; r.k0 = (q >> 7) * 64; r.n0 = (q & 127) * 32; }
; __device__ __forceinline__ void side_transpose(KP p, char* smem, int bid, int nb, int wv, const int part) {
;     ...
;   const int all = 64 * 128 + 64 * 688;
;   const int tot = (all / 4) * (part + 1);
;   const int stride = nb * 6;
;   int j = (all / 4) * part + bid * 6 + (wv - 2);
;   if (j >= tot) return;
;   SideJob cur = side_job(p, j);
.LBB0_885:
	v_readlane_b32 s4, v253, 42
	s_mulk_i32 s4, 0x3300
	v_readlane_b32 s5, v253, 17
	s_add_i32 s26, s4, 0x3300
	s_add_i32 s27, s4, s5
	s_mov_b64 s[14:15], s[86:87]
	s_and_b32 s4, s5, 1
	s_cmp_lg_u32 s4, 0
	s_cselect_b32 s27, s26, s27
	s_cmp_ge_i32 s27, s26
	v_mbcnt_lo_u32_b32 v10, -1, 0
	v_mbcnt_hi_u32_b32 v10, -1, v10
	s_cbranch_scc1 .LBB0_898
	s_add_u32 s10, s14, 0x48
	s_addc_u32 s11, s15, 0
	s_add_u32 s6, s14, 0x90
	s_addc_u32 s7, s15, 0
	s_cmpk_gt_i32 s27, 0x1fff
	s_cbranch_scc0 .LBB0_888
	s_add_u32 s10, s14, 0x58
	s_addc_u32 s11, s15, 0
	s_add_u32 s6, s14, 0x98
	s_addc_u32 s7, s15, 0
	s_add_i32 s5, s27, 0xe000
	s_and_b32 s4, s5, 0xffff
	s_mul_i32 s4, s4, 0xbe83
	s_lshr_b32 s8, s4, 25
	s_lshl_b32 s4, s8, 6
	s_mulk_i32 s8, 0x2b0
	s_sub_i32 s5, s5, s8
	s_lshl_b32 s5, s5, 5
	s_and_b32 s42, s5, 0xffe0
	s_mov_b64 s[8:9], 0x5600
	s_cbranch_execz .LBB0_889
	s_branch .LBB0_890

; __global__ void __launch_bounds__(NT) mega(Params pv) {
;     ...
; #pragma unroll
;   for (int seg = 0; seg < 4; ++seg) {
;     if (wv < 2) {
;       KP p = kparams();
;       __builtin_amdgcn_s_setprio(3);
;       for (int t0 = bid; t0 < 256; t0 += nb) {
;         const int t = (nb == 256) ? ((t0 & 7) * 32 + (t0 >> 3)) : t0;
;         if (wv == 0) hgrn_seq_task(p, smem, t, wv, seg * 64, seg * 64 + 64);
;         else gdn_seq_task(p, smem, t, wv, seg * 64, seg * 64 + 64);
;       }
;       __builtin_amdgcn_s_setprio(0);
;     } else {
;       char* wa = smem + WORK_OFF + (wv - 2) * WLDS_B;
;       if (seg < 3) {
;         { KP p = kparams(); hgrn_pre_phase(p, wa, wv, seg + 1, bid * 6 + (wv - 2), nb * 6); }
;         { KP p = kparams(); gdn_pre_phase(p, wa, wv, seg + 1, bid * 6 + (wv - 2), nb * 6); }
;       }
;       { KP p = kparams(); side_transpose(p, smem, bid, nb, wv, seg); }
;       if (seg > 0) { KP p = kparams(); headnorm_phase(p, wv, seg - 1, bid * 6 + (wv - 2), nb * 6); }
;     }
;     xcd_barrier(xb, wv, bgen);
.LBB0_990:
	s_or_b64 exec, exec, s[4:5]
	v_readlane_b32 s4, v253, 42
	s_or_b32 s34, s4, 1
	v_readlane_b32 s4, v253, 11
	v_readlane_b32 s5, v253, 12
	s_andn2_b64 vcc, exec, s[4:5]
	s_mov_b64 s[4:5], -1
	s_waitcnt lgkmcnt(0)
	s_barrier
	s_cbranch_vccnz .LBB0_1045
	v_readlane_b32 s4, v253, 17
	s_nop 3
	s_and_b32 s4, s4, 1
	s_cmp_eq_u32 s4, 0
	s_cbranch_scc1 .Ld2_done

; #define tidx() tidx_(wv)
; __device__ __forceinline__ void hgrn_pre_phase(KP p, char* smem, int wv, const int seg, const int gw, const int nw) {
;   const int lane = tidx() & 63, fr = lane & 15, fq = lane >> 4;
;   unsigned short* wl = (unsigned short*)smem;
;   char* scr = (char*)p->Wt1;
;   for (int idx = gw; idx < 2048; idx += nw) {
;     const int bh = idx >> 6, c = seg * 64 + (idx & 63), task = bh * 256 + c, b = bh >> 4, h = bh & 15;
;     const long r0 = (long)b * SEQ + c * 16;
;     const float* qsrc = p->proj + r0 * PW + h * 128 + lane * 2;
;     float2 qv[16], fv[16];
; #pragma unroll
;     for (int i = 0; i < 16; ++i) { qv[i] = *(const float2*)(qsrc + (long)i * PW); fv[i] = *(const float2*)(qsrc + 2048 + (long)i * PW); }
;     float lb0[16], lb1[16];
;     float c0 = 0.f, c1 = 0.f;
; #pragma unroll
;     for (int i = 0; i < 16; ++i) { c0 += __logf(fv[i].x); c1 += __logf(fv[i].y); lb0[i] = c0; lb1[i] = c1; }
;     char* tb = scr + (long)task * HG_TASK_B;
;     *(float2*)(tb + 8704 + lane * 8) = make_float2(__expf(c0), __expf(c1));
;     unsigned short kh0[16], kh1[16];
;     const float ec0 = __expf(c0), ec1 = __expf(c1);
; #pragma unroll
;     for (int i = 0; i < 16; ++i) {
;       const float e0 = __expf(lb0[i]), e1 = __expf(lb1[i]);
;       const float k0 = (1.f - fv[i].x) * __frcp_rn(e0), k1 = (1.f - fv[i].y) * __frcp_rn(e1);
;       const unsigned qt = (unsigned)f2bf(qv[i].x * e0) | ((unsigned)f2bf(qv[i].y * e1) << 16);
;       const unsigned kt = (unsigned)f2bf(k0) | ((unsigned)f2bf(k1) << 16);
;       *(unsigned*)(wl + i * 136 + lane * 2) = qt;
;       *(unsigned*)(wl + 2176 + i * 136 + lane * 2) = kt;
; __global__ void __launch_bounds__(NT) mega(Params pv) {
;     ...
;       if (seg < 3) {
;         { KP p = kparams(); hgrn_pre_phase(p, wa, wv, seg + 1, bid * 6 + (wv - 2), nb * 6); }
.Ld2_done:
	v_readlane_b32 s4, v253, 42
	s_cmp_eq_u32 s4, 2
	s_cbranch_scc1 .LBB0_1028
	v_readlane_b32 s6, v253, 42
	s_add_i32 s0, s6, 2
	v_readlane_b32 s6, v253, 49
	v_readlane_b32 s7, v253, 50
	s_mov_b64 s[4:5], s[86:87]
	s_and_b64 vcc, exec, s[6:7]
	s_mov_b32 s1, 0x10000
	s_mov_b32 s2, 0x1c000
	s_mov_b32 s3, 0x1e000
	s_mov_b32 s35, 0x2a000
	s_mov_b32 s40, 0x2c000
	s_mov_b32 s29, 0x38000
	s_mov_b32 s41, 0x3a000
	s_mov_b32 s36, 0x46000
	s_mov_b32 s37, 0x48000
	s_mov_b32 s42, 0x54000
	s_mov_b32 s44, 0x56000
	s_mov_b32 s45, 0x62000
	s_mov_b32 s50, 0x64000
	s_mov_b32 s51, 0x70000
	s_mov_b32 s52, 0x72000
	s_mov_b32 s82, 0x7e000
	s_mov_b32 s83, 0x80000
	s_mov_b32 s88, 0x8c000
	s_mov_b32 s89, 0x8e000
	s_mov_b32 s90, 0x9a000
	s_mov_b32 s91, 0x9c000
	s_mov_b32 s92, 0xa8000
	s_mov_b32 s93, 0xaa000
	s_mov_b32 s94, 0xb6000
	s_mov_b32 s95, 0xb8000
	s_mov_b32 s20, 0xc4000
	s_mov_b32 s25, 0xc6000
	s_mov_b32 s26, 0xd2000
	s_mov_b32 s27, 0xd4000
	s_movk_i32 s28, 0x1000
	s_mov_b64 s[30:31], 0x1000
	v_mbcnt_lo_u32_b32 v0, -1, 0
	v_mbcnt_hi_u32_b32 v0, -1, v0
	s_cbranch_vccnz .LBB0_995
	v_and_b32_e32 v4, 63, v0
	v_lshlrev_b32_e32 v2, 1, v4
	v_lshlrev_b32_e32 v5, 2, v0
	v_and_b32_e32 v6, 14, v2
	s_movk_i32 s6, 0xe0
	v_and_b32_e32 v3, 15, v0
	v_and_or_b32 v5, v5, s6, v6
	s_load_dwordx2 s[16:17], s[4:5], 0x88
	s_load_dwordx2 s[18:19], s[4:5], 0xc0
	v_readlane_b32 s5, v253, 13
	v_lshlrev_b32_e32 v20, 4, v5
	v_mul_u32_u24_e32 v5, 0x88, v3
	v_lshlrev_b32_e32 v18, 3, v4
	v_lshl_add_u32 v74, v4, 2, s5
	v_lshlrev_b32_e32 v5, 1, v5
	v_and_b32_e32 v6, 48, v0
	v_lshlrev_b32_e32 v22, 4, v4
	v_lshrrev_b32_e32 v4, 2, v0
	v_add3_u32 v75, s5, v5, v6
	v_and_b32_e32 v5, 12, v4
	v_lshlrev_b32_e32 v4, 1, v0
	v_and_b32_e32 v7, 16, v4
	v_cmp_gt_u32_e64 s[6:7], v3, v5
	v_or_b32_e32 v4, v5, v7
	v_or_b32_e32 v6, 1, v5
	v_or_b32_e32 v8, 2, v5
	v_or_b32_e32 v5, 3, v5
	v_and_b32_e32 v0, 7, v0
	v_cmp_gt_u32_e64 s[8:9], v3, v6
	v_or_b32_e32 v6, v6, v7
	v_cmp_gt_u32_e64 s[10:11], v3, v8
	v_or_b32_e32 v8, v8, v7
	v_cmp_gt_u32_e64 s[12:13], v3, v5
	v_or_b32_e32 v3, v5, v7
	v_lshl_or_b32 v4, v4, 3, v0
	v_lshl_or_b32 v6, v6, 3, v0
	v_lshl_or_b32 v8, v8, 3, v0
	v_lshl_or_b32 v10, v3, 3, v0
	s_lshl_b32 s4, s0, 6
	v_mov_b32_e32 v19, v1
	v_mov_b32_e32 v21, v1
	v_mov_b32_e32 v23, v1
	v_lshlrev_b32_e32 v0, 2, v2
	v_lshlrev_b32_e32 v76, 1, v4
	v_lshlrev_b32_e32 v77, 1, v6
	v_lshlrev_b32_e32 v78, 1, v8
	v_lshlrev_b32_e32 v79, 1, v10
	v_readlane_b32 s5, v253, 17

; __device__ __forceinline__ SideJob side_job(KP p, const int j) {
;   const int t2 = 64 * 128, t3 = 64 * 688;
;   SideJob r;
;   if (j < t2) { r.W = p->w_out; r.Wt = p->Wt2; r.K = D; r.N = D; r.k0 = (j >> 7) * 64; r.n0 = (j & 127) * 32; }
;   else if (j < t2 + t3) { const int q = j - t2; r.W = p->w_ffn_in; r.Wt = p->Wt3; r.K = D; r.N = DFF2; r.k0 = (q / 688) * 64; r.n0 = (q % 688) * 32; }
;   else { const int q = j - t2 - t3; r.W = p->w_ffn_out; r.Wt = p->Wt4; r.K = DFF; r.N = D; r.k0 = (q >> 7) * 64; r.n0 = (q & 127) * 32; }
; __device__ __forceinline__ void side_transpose(KP p, char* smem, int bid, int nb, int wv, const int part) {
;     ...
;   const int all = 64 * 128 + 64 * 688;
;   const int tot = (all / 4) * (part + 1);
;   const int stride = nb * 6;
;   int j = (all / 4) * part + bid * 6 + (wv - 2);
;   if (j >= tot) return;
;   SideJob cur = side_job(p, j);
.LBB0_1028:
	s_mul_i32 s4, s34, 0x3300
	v_readlane_b32 s5, v253, 17
	s_add_i32 s26, s4, 0x3300
	s_add_i32 s27, s4, s5
	s_mov_b64 s[14:15], s[86:87]
	s_and_b32 s4, s5, 1
	s_cmp_lg_u32 s4, 0
	s_cselect_b32 s27, s26, s27
	s_cmp_ge_i32 s27, s26
	v_readlane_b32 s36, v253, 14
	v_readlane_b32 s37, v253, 15
	v_mbcnt_lo_u32_b32 v10, -1, 0
	v_mbcnt_hi_u32_b32 v10, -1, v10
	s_cbranch_scc1 .LBB0_1041
	s_add_u32 s10, s14, 0x48
	s_addc_u32 s11, s15, 0
	s_add_u32 s6, s14, 0x90
	s_addc_u32 s7, s15, 0
	s_cmpk_lt_i32 s27, 0x2000
	s_cbranch_scc1 .LBB0_1031
	s_add_u32 s10, s14, 0x58
	s_addc_u32 s11, s15, 0
	s_add_u32 s6, s14, 0x98
	s_addc_u32 s7, s15, 0
	s_add_i32 s5, s27, 0xe000
	s_and_b32 s4, s5, 0xffff
	s_mul_i32 s4, s4, 0xbe83
	s_lshr_b32 s8, s4, 25
	s_lshl_b32 s4, s8, 6
	s_mulk_i32 s8, 0x2b0
	s_sub_i32 s5, s5, s8
	s_lshl_b32 s5, s5, 5
	s_and_b32 s42, s5, 0xffe0
	s_mov_b64 s[8:9], 0x5600
	s_cbranch_execz .LBB0_1032
	s_branch .LBB0_1033
